# E1 and E2 GEMM k-loops re-interleaved by hand like the phase A loop: same instructions, staging writes/loads and fragment reads spread over the MFMA gaps, waits recomputed (E2 with its own address tem
# baseline (speedup 1.0000x reference)
.LBB0_50:
	v_add_u32_e32 v40, v12, v13
	ds_read_b128 v[28:31], v40
	ds_read_b128 v[32:35], v40 offset:32
	ds_read_b128 v[164:167], v40 offset:4608
	ds_read_b128 v[168:171], v40 offset:4640
	ds_read_b128 v[172:175], v40 offset:9216
	ds_read_b128 v[176:179], v40 offset:9248
	ds_read_b128 v[180:183], v40 offset:13824
	ds_read_b128 v[184:187], v40 offset:13856
	v_add_u32_e32 v206, v12, v14
	ds_read_b128 v[188:191], v206 offset:36864
	ds_read_b128 v[192:195], v206 offset:36896
	ds_read_b128 v[196:199], v206 offset:41472
	ds_read_b128 v[200:203], v206 offset:41504
	s_add_i32 s2, s2, 2
	s_sub_i32 s8, s3, 64
	s_cmp_lt_u32 s2, 13
	s_cselect_b32 s90, s8, 0
	s_lshl_b64 s[8:9], s[90:91], 1
	v_lshl_add_u64 v[36:37], v[0:1], 0, s[8:9]
	v_lshl_add_u64 v[204:205], v[2:3], 0, s[8:9]
	s_waitcnt lgkmcnt(3)
	v_mfma_f32_32x32x16_f16 a[96:111], v[28:31], v[188:191], a[96:111]
	v_lshl_add_u64 v[208:209], v[36:37], 0, v[18:19]
	v_lshl_add_u64 v[210:211], v[36:37], 0, v[20:21]
	v_lshl_add_u64 v[212:213], v[204:205], 0, v[18:19]
	v_lshl_add_u64 v[214:215], v[36:37], 0, v[22:23]
	s_waitcnt lgkmcnt(1)
	v_mfma_f32_32x32x16_f16 a[112:127], v[28:31], v[196:199], a[112:127]
	s_waitcnt vmcnt(23)
	ds_write_b128 v61, v[64:67] offset:55296
	global_load_dwordx4 v[64:67], v[208:209], off
	v_mfma_f32_32x32x16_f16 a[64:79], v[164:167], v[188:191], a[64:79]
	ds_read_b128 v[28:31], v40 offset:64
	v_lshl_add_u64 v[216:217], v[36:37], 0, v[24:25]
	v_lshl_add_u64 v[218:219], v[204:205], 0, v[20:21]
	v_mfma_f32_32x32x16_f16 a[80:95], v[164:167], v[196:199], a[80:95]
	s_waitcnt vmcnt(23)
	ds_write_b128 v61, v[68:71] offset:59904
	global_load_dwordx4 v[68:71], v[210:211], off
	v_mfma_f32_32x32x16_f16 a[32:47], v[172:175], v[188:191], a[32:47]
	ds_read_b128 v[164:167], v40 offset:4672
	v_lshl_add_u64 v[220:221], v[36:37], 0, v[4:5]
	v_lshl_add_u64 v[222:223], v[36:37], 0, v[6:7]
	v_mfma_f32_32x32x16_f16 a[48:63], v[172:175], v[196:199], a[48:63]
	s_waitcnt vmcnt(17)
	ds_write_b128 v15, v[100:103]
	global_load_dwordx4 v[100:103], v[212:213], off
	v_mfma_f32_32x32x16_f16 a[0:15], v[180:183], v[188:191], a[0:15]
	ds_read_b128 v[172:175], v40 offset:9280
	ds_read_b128 v[188:191], v206 offset:36928
	v_lshl_add_u64 v[208:209], v[204:205], 0, v[22:23]
	v_mfma_f32_32x32x16_f16 a[16:31], v[180:183], v[196:199], a[16:31]
	ds_read_b128 v[180:183], v40 offset:13888
	ds_read_b128 v[196:199], v206 offset:41536
	v_lshl_add_u64 v[210:211], v[36:37], 0, v[8:9]
	v_mfma_f32_32x32x16_f16 a[96:111], v[32:35], v[192:195], a[96:111]
	ds_write_b128 v61, v[72:75] offset:64512
	global_load_dwordx4 v[72:75], v[214:215], off
	s_waitcnt lgkmcnt(10)
	v_mfma_f32_32x32x16_f16 a[112:127], v[32:35], v[200:203], a[112:127]
	ds_read_b128 v[32:35], v40 offset:96
	v_lshl_add_u64 v[212:213], v[36:37], 0, v[10:11]
	v_lshl_add_u64 v[214:215], v[204:205], 0, v[24:25]
	v_mfma_f32_32x32x16_f16 a[64:79], v[168:171], v[192:195], a[64:79]
	ds_write_b128 v62, v[76:79] offset:55296
	global_load_dwordx4 v[76:79], v[216:217], off
	v_mfma_f32_32x32x16_f16 a[80:95], v[168:171], v[200:203], a[80:95]
	ds_read_b128 v[168:171], v40 offset:4704
	v_mfma_f32_32x32x16_f16 a[32:47], v[176:179], v[192:195], a[32:47]
	s_waitcnt vmcnt(19)
	ds_write_b128 v15, v[104:107] offset:4608
	global_load_dwordx4 v[104:107], v[218:219], off
	v_mfma_f32_32x32x16_f16 a[48:63], v[176:179], v[200:203], a[48:63]
	ds_read_b128 v[176:179], v40 offset:9312
	v_mfma_f32_32x32x16_f16 a[0:15], v[184:187], v[192:195], a[0:15]
	ds_read_b128 v[192:195], v206 offset:36960
	v_mfma_f32_32x32x16_f16 a[16:31], v[184:187], v[200:203], a[16:31]
	ds_read_b128 v[184:187], v40 offset:13920
	ds_read_b128 v[200:203], v206 offset:41568
	ds_write_b128 v62, v[84:87] offset:59904
	s_waitcnt lgkmcnt(12)
	v_mfma_f32_32x32x16_f16 a[96:111], v[28:31], v[188:191], a[96:111]
	global_load_dwordx4 v[84:87], v[220:221], off
	s_waitcnt lgkmcnt(10)
	v_mfma_f32_32x32x16_f16 a[112:127], v[28:31], v[196:199], a[112:127]
	ds_write_b128 v62, v[88:91] offset:64512
	global_load_dwordx4 v[88:91], v[222:223], off
	v_mfma_f32_32x32x16_f16 a[64:79], v[164:167], v[188:191], a[64:79]
	v_mfma_f32_32x32x16_f16 a[80:95], v[164:167], v[196:199], a[80:95]
	s_waitcnt vmcnt(21)
	ds_write_b128 v15, v[108:111] offset:9216
	global_load_dwordx4 v[108:111], v[208:209], off
	v_mfma_f32_32x32x16_f16 a[32:47], v[172:175], v[188:191], a[32:47]
	v_mfma_f32_32x32x16_f16 a[48:63], v[172:175], v[196:199], a[48:63]
	v_mfma_f32_32x32x16_f16 a[0:15], v[180:183], v[188:191], a[0:15]
	ds_write_b128 v63, v[92:95] offset:59904
	global_load_dwordx4 v[92:95], v[210:211], off
	v_mfma_f32_32x32x16_f16 a[16:31], v[180:183], v[196:199], a[16:31]
	s_waitcnt lgkmcnt(6)
	v_mfma_f32_32x32x16_f16 a[96:111], v[32:35], v[192:195], a[96:111]
	ds_write_b128 v63, v[96:99] offset:64512
	global_load_dwordx4 v[96:99], v[212:213], off
	s_waitcnt lgkmcnt(5)
	v_mfma_f32_32x32x16_f16 a[112:127], v[32:35], v[200:203], a[112:127]
	v_mfma_f32_32x32x16_f16 a[64:79], v[168:171], v[192:195], a[64:79]
	s_waitcnt vmcnt(23)
	ds_write_b128 v15, v[112:115] offset:13824
	global_load_dwordx4 v[112:115], v[214:215], off
	v_mfma_f32_32x32x16_f16 a[80:95], v[168:171], v[200:203], a[80:95]
	v_mfma_f32_32x32x16_f16 a[32:47], v[176:179], v[192:195], a[32:47]
	v_mfma_f32_32x32x16_f16 a[48:63], v[176:179], v[200:203], a[48:63]
	v_mfma_f32_32x32x16_f16 a[0:15], v[184:187], v[192:195], a[0:15]
	v_mfma_f32_32x32x16_f16 a[16:31], v[184:187], v[200:203], a[16:31]
	s_waitcnt lgkmcnt(0)
	s_barrier
	ds_read_b128 v[28:31], v40 offset:55296
	ds_read_b128 v[32:35], v40 offset:55328
	ds_read_b128 v[164:167], v40 offset:59904
	ds_read_b128 v[168:171], v40 offset:59936
	ds_read_b128 v[172:175], v40 offset:64512
	ds_read_b128 v[176:179], v40 offset:64544
	ds_read_b128 v[180:183], v26 offset:55296
	ds_read_b128 v[184:187], v26 offset:55328
	ds_read_b128 v[188:191], v27
	ds_read_b128 v[192:195], v27 offset:32
	ds_read_b128 v[196:199], v27 offset:4608
	ds_read_b128 v[200:203], v27 offset:4640
	s_cmp_lt_u32 s2, 12
	s_cselect_b32 s90, s3, 0
	s_lshl_b64 s[8:9], s[90:91], 1
	v_lshl_add_u64 v[36:37], v[0:1], 0, s[8:9]
	v_lshl_add_u64 v[204:205], v[2:3], 0, s[8:9]
	s_waitcnt lgkmcnt(3)
	v_mfma_f32_32x32x16_f16 a[96:111], v[28:31], v[188:191], a[96:111]
	v_lshl_add_u64 v[208:209], v[36:37], 0, v[18:19]
	v_lshl_add_u64 v[210:211], v[36:37], 0, v[20:21]
	v_lshl_add_u64 v[212:213], v[204:205], 0, v[18:19]
	v_lshl_add_u64 v[214:215], v[36:37], 0, v[22:23]
	s_waitcnt lgkmcnt(1)
	v_mfma_f32_32x32x16_f16 a[112:127], v[28:31], v[196:199], a[112:127]
	s_waitcnt vmcnt(23)
	ds_write_b128 v61, v[116:119]
	global_load_dwordx4 v[116:119], v[208:209], off
	v_mfma_f32_32x32x16_f16 a[64:79], v[164:167], v[188:191], a[64:79]
	ds_read_b128 v[28:31], v40 offset:55360
	v_lshl_add_u64 v[216:217], v[36:37], 0, v[24:25]
	v_lshl_add_u64 v[218:219], v[204:205], 0, v[20:21]
	v_mfma_f32_32x32x16_f16 a[80:95], v[164:167], v[196:199], a[80:95]
	s_waitcnt vmcnt(23)
	ds_write_b128 v61, v[120:123] offset:4608
	global_load_dwordx4 v[120:123], v[210:211], off
	v_mfma_f32_32x32x16_f16 a[32:47], v[172:175], v[188:191], a[32:47]
	ds_read_b128 v[164:167], v40 offset:59968
	v_lshl_add_u64 v[220:221], v[36:37], 0, v[4:5]
	v_lshl_add_u64 v[222:223], v[36:37], 0, v[6:7]
	v_mfma_f32_32x32x16_f16 a[48:63], v[172:175], v[196:199], a[48:63]
	s_waitcnt vmcnt(15)
	ds_write_b128 v61, v[148:151] offset:36864
	global_load_dwordx4 v[148:151], v[212:213], off
	v_mfma_f32_32x32x16_f16 a[0:15], v[180:183], v[188:191], a[0:15]
	ds_read_b128 v[172:175], v40 offset:64576
	ds_read_b128 v[188:191], v27 offset:64
	v_lshl_add_u64 v[208:209], v[204:205], 0, v[22:23]
	v_mfma_f32_32x32x16_f16 a[16:31], v[180:183], v[196:199], a[16:31]
	ds_read_b128 v[180:183], v26 offset:55360
	ds_read_b128 v[196:199], v27 offset:4672
	v_lshl_add_u64 v[210:211], v[36:37], 0, v[8:9]
	v_mfma_f32_32x32x16_f16 a[96:111], v[32:35], v[192:195], a[96:111]
	ds_write_b128 v61, v[124:127] offset:9216
	global_load_dwordx4 v[124:127], v[214:215], off
	s_waitcnt lgkmcnt(10)
	v_mfma_f32_32x32x16_f16 a[112:127], v[32:35], v[200:203], a[112:127]
	ds_read_b128 v[32:35], v40 offset:55392
	v_lshl_add_u64 v[212:213], v[36:37], 0, v[10:11]
	v_lshl_add_u64 v[214:215], v[204:205], 0, v[24:25]
	v_mfma_f32_32x32x16_f16 a[64:79], v[168:171], v[192:195], a[64:79]
	ds_write_b128 v61, v[128:131] offset:13824
	global_load_dwordx4 v[128:131], v[216:217], off
	v_mfma_f32_32x32x16_f16 a[80:95], v[168:171], v[200:203], a[80:95]
	ds_read_b128 v[168:171], v40 offset:60000
	v_mfma_f32_32x32x16_f16 a[32:47], v[176:179], v[192:195], a[32:47]
	ds_write_b128 v61, v[152:155] offset:41472
	global_load_dwordx4 v[152:155], v[218:219], off
	v_mfma_f32_32x32x16_f16 a[48:63], v[176:179], v[200:203], a[48:63]
	ds_read_b128 v[176:179], v40 offset:64608
	v_mfma_f32_32x32x16_f16 a[0:15], v[184:187], v[192:195], a[0:15]
	ds_read_b128 v[192:195], v27 offset:96
	v_mfma_f32_32x32x16_f16 a[16:31], v[184:187], v[200:203], a[16:31]
	ds_read_b128 v[184:187], v26 offset:55392
	ds_read_b128 v[200:203], v27 offset:4704
	ds_write_b128 v61, v[132:135] offset:18432
	s_waitcnt lgkmcnt(12)
	v_mfma_f32_32x32x16_f16 a[96:111], v[28:31], v[188:191], a[96:111]
	global_load_dwordx4 v[132:135], v[220:221], off
	s_waitcnt lgkmcnt(10)
	v_mfma_f32_32x32x16_f16 a[112:127], v[28:31], v[196:199], a[112:127]
	ds_write_b128 v61, v[136:139] offset:23040
	global_load_dwordx4 v[136:139], v[222:223], off
	v_mfma_f32_32x32x16_f16 a[64:79], v[164:167], v[188:191], a[64:79]
	v_mfma_f32_32x32x16_f16 a[80:95], v[164:167], v[196:199], a[80:95]
	ds_write_b128 v61, v[156:159] offset:46080
	global_load_dwordx4 v[156:159], v[208:209], off
	v_mfma_f32_32x32x16_f16 a[32:47], v[172:175], v[188:191], a[32:47]
	v_mfma_f32_32x32x16_f16 a[48:63], v[172:175], v[196:199], a[48:63]
	v_mfma_f32_32x32x16_f16 a[0:15], v[180:183], v[188:191], a[0:15]
	ds_write_b128 v61, v[140:143] offset:27648
	global_load_dwordx4 v[140:143], v[210:211], off
	v_mfma_f32_32x32x16_f16 a[16:31], v[180:183], v[196:199], a[16:31]
	s_waitcnt lgkmcnt(6)
	v_mfma_f32_32x32x16_f16 a[96:111], v[32:35], v[192:195], a[96:111]
	ds_write_b128 v61, v[144:147] offset:32256
	global_load_dwordx4 v[144:147], v[212:213], off
	s_waitcnt lgkmcnt(5)
	v_mfma_f32_32x32x16_f16 a[112:127], v[32:35], v[200:203], a[112:127]
	v_mfma_f32_32x32x16_f16 a[64:79], v[168:171], v[192:195], a[64:79]
	s_waitcnt vmcnt(23)
	ds_write_b128 v61, v[160:163] offset:50688
	global_load_dwordx4 v[160:163], v[214:215], off
	v_mfma_f32_32x32x16_f16 a[80:95], v[168:171], v[200:203], a[80:95]
	v_mfma_f32_32x32x16_f16 a[32:47], v[176:179], v[192:195], a[32:47]
	v_mfma_f32_32x32x16_f16 a[48:63], v[176:179], v[200:203], a[48:63]
	v_mfma_f32_32x32x16_f16 a[0:15], v[184:187], v[192:195], a[0:15]
	v_mfma_f32_32x32x16_f16 a[16:31], v[184:187], v[200:203], a[16:31]
	s_waitcnt lgkmcnt(0)
	s_barrier
	s_addk_i32 s3, 0x80
	s_cmp_lt_u32 s2, 14
	s_cbranch_scc1 .LBB0_50
	ds_write_b32 v45, a96
	s_nop 0
	ds_write_b32 v46, a112
	ds_write_b32 v45, a97 offset:272
	ds_write_b32 v46, a113 offset:272
	ds_write_b32 v45, a98 offset:544
	ds_write_b32 v46, a114 offset:544
	ds_write_b32 v47, a99
	ds_write_b32 v48, a115
	ds_write_b32 v45, a100 offset:2176
	ds_write_b32 v46, a116 offset:2176
	ds_write_b32 v45, a101 offset:2448
	ds_write_b32 v46, a117 offset:2448
	ds_write_b32 v45, a102 offset:2720
	ds_write_b32 v46, a118 offset:2720
	ds_write_b32 v49, a103
	ds_write_b32 v50, a119
	ds_write_b32 v45, a104 offset:4352
	ds_write_b32 v46, a120 offset:4352
	ds_write_b32 v45, a105 offset:4624
	ds_write_b32 v46, a121 offset:4624
	ds_write_b32 v45, a106 offset:4896
	ds_write_b32 v46, a122 offset:4896
	ds_write_b32 v51, a107
	ds_write_b32 v52, a123
	ds_write_b32 v45, a108 offset:6528
	ds_write_b32 v46, a124 offset:6528
	ds_write_b32 v45, a109 offset:6800
	ds_write_b32 v46, a125 offset:6800
	ds_write_b32 v45, a110 offset:7072
	ds_write_b32 v46, a126 offset:7072
	ds_write_b32 v53, a111
	ds_write_b32 v54, a127
	v_lshl_add_u32 v12, v60, 8, v42
	ds_read_b128 v[2:5], v58
	ds_read_b128 v[6:9], v58 offset:16
	v_lshl_or_b32 v0, v59, 7, v43
	v_or_b32_e32 v10, v12, v44
	v_ashrrev_i32_e32 v1, 31, v0
	v_ashrrev_i32_e32 v11, 31, v10
	v_lshl_add_u64 v[0:1], v[0:1], 2, v[16:17]
	v_lshlrev_b64 v[10:11], 12, v[10:11]
	v_lshl_add_u64 v[10:11], v[0:1], 0, v[10:11]
	s_waitcnt lgkmcnt(1)
	global_store_dwordx4 v[10:11], v[2:5], off
	s_waitcnt lgkmcnt(0)
	global_store_dwordx4 v[10:11], v[6:9], off offset:16
	ds_read_b128 v[2:5], v58 offset:2176
	ds_read_b128 v[6:9], v58 offset:2192
	v_or_b32_e32 v10, v12, v55
	v_ashrrev_i32_e32 v11, 31, v10
	v_lshlrev_b64 v[10:11], 12, v[10:11]
	v_lshl_add_u64 v[10:11], v[0:1], 0, v[10:11]
	s_waitcnt lgkmcnt(1)
	global_store_dwordx4 v[10:11], v[2:5], off
	s_waitcnt lgkmcnt(0)
	global_store_dwordx4 v[10:11], v[6:9], off offset:16
	ds_read_b128 v[2:5], v58 offset:4352
	ds_read_b128 v[6:9], v58 offset:4368
	v_or_b32_e32 v10, v12, v56
	v_ashrrev_i32_e32 v11, 31, v10
	v_lshlrev_b64 v[10:11], 12, v[10:11]
	v_lshl_add_u64 v[10:11], v[0:1], 0, v[10:11]
	s_waitcnt lgkmcnt(1)
	global_store_dwordx4 v[10:11], v[2:5], off
	s_waitcnt lgkmcnt(0)
	global_store_dwordx4 v[10:11], v[6:9], off offset:16
	ds_read_b128 v[2:5], v58 offset:6528
	ds_read_b128 v[6:9], v58 offset:6544
	v_or_b32_e32 v10, v12, v57
	v_ashrrev_i32_e32 v11, 31, v10
	v_lshlrev_b64 v[10:11], 12, v[10:11]
	v_lshl_add_u64 v[10:11], v[0:1], 0, v[10:11]
	s_waitcnt lgkmcnt(1)
	global_store_dwordx4 v[10:11], v[2:5], off
	s_waitcnt lgkmcnt(0)
	global_store_dwordx4 v[10:11], v[6:9], off offset:16
	ds_write_b32 v45, a64
	ds_write_b32 v46, a80
	ds_write_b32 v45, a65 offset:272
	ds_write_b32 v46, a81 offset:272
	ds_write_b32 v45, a66 offset:544
	ds_write_b32 v46, a82 offset:544
	ds_write_b32 v47, a67
	ds_write_b32 v48, a83
	ds_write_b32 v45, a68 offset:2176
	ds_write_b32 v46, a84 offset:2176
	ds_write_b32 v45, a69 offset:2448
	ds_write_b32 v46, a85 offset:2448
	ds_write_b32 v45, a70 offset:2720
	ds_write_b32 v46, a86 offset:2720
	ds_write_b32 v49, a71
	ds_write_b32 v50, a87
	ds_write_b32 v45, a72 offset:4352
	ds_write_b32 v46, a88 offset:4352
	ds_write_b32 v45, a73 offset:4624
	ds_write_b32 v46, a89 offset:4624
	ds_write_b32 v45, a74 offset:4896
	ds_write_b32 v46, a90 offset:4896
	ds_write_b32 v51, a75
	ds_write_b32 v52, a91
	ds_write_b32 v45, a76 offset:6528
	ds_write_b32 v46, a92 offset:6528
	ds_write_b32 v45, a77 offset:6800
	ds_write_b32 v46, a93 offset:6800
	ds_write_b32 v45, a78 offset:7072
	ds_write_b32 v46, a94 offset:7072
	ds_write_b32 v53, a79
	ds_write_b32 v54, a95
	v_or_b32_e32 v13, 32, v12
	ds_read_b128 v[2:5], v58
	ds_read_b128 v[6:9], v58 offset:16
	v_or_b32_e32 v10, v13, v44
	v_ashrrev_i32_e32 v11, 31, v10
	v_lshlrev_b64 v[10:11], 12, v[10:11]
	v_lshl_add_u64 v[10:11], v[0:1], 0, v[10:11]
	s_waitcnt lgkmcnt(1)
	global_store_dwordx4 v[10:11], v[2:5], off
	s_waitcnt lgkmcnt(0)
	global_store_dwordx4 v[10:11], v[6:9], off offset:16
	ds_read_b128 v[2:5], v58 offset:2176
	ds_read_b128 v[6:9], v58 offset:2192
	v_or_b32_e32 v10, v13, v55
	v_ashrrev_i32_e32 v11, 31, v10
	v_lshlrev_b64 v[10:11], 12, v[10:11]
	v_lshl_add_u64 v[10:11], v[0:1], 0, v[10:11]
	s_waitcnt lgkmcnt(1)
	global_store_dwordx4 v[10:11], v[2:5], off
	s_waitcnt lgkmcnt(0)
	global_store_dwordx4 v[10:11], v[6:9], off offset:16
	ds_read_b128 v[2:5], v58 offset:4352
	ds_read_b128 v[6:9], v58 offset:4368
	v_or_b32_e32 v10, v13, v56
	v_ashrrev_i32_e32 v11, 31, v10
	v_lshlrev_b64 v[10:11], 12, v[10:11]
	v_lshl_add_u64 v[10:11], v[0:1], 0, v[10:11]
	s_waitcnt lgkmcnt(1)
	global_store_dwordx4 v[10:11], v[2:5], off
	s_waitcnt lgkmcnt(0)
	global_store_dwordx4 v[10:11], v[6:9], off offset:16
	ds_read_b128 v[2:5], v58 offset:6528
	ds_read_b128 v[6:9], v58 offset:6544
	v_or_b32_e32 v10, v13, v57
	v_ashrrev_i32_e32 v11, 31, v10
	v_lshlrev_b64 v[10:11], 12, v[10:11]
	v_lshl_add_u64 v[10:11], v[0:1], 0, v[10:11]
	s_waitcnt lgkmcnt(1)
	global_store_dwordx4 v[10:11], v[2:5], off
	s_waitcnt lgkmcnt(0)
	global_store_dwordx4 v[10:11], v[6:9], off offset:16
	ds_write_b32 v45, a32
	ds_write_b32 v46, a48
	ds_write_b32 v45, a33 offset:272
	ds_write_b32 v46, a49 offset:272
	ds_write_b32 v45, a34 offset:544
	ds_write_b32 v46, a50 offset:544
	ds_write_b32 v47, a35
	ds_write_b32 v48, a51
	ds_write_b32 v45, a36 offset:2176
	ds_write_b32 v46, a52 offset:2176
	ds_write_b32 v45, a37 offset:2448
	ds_write_b32 v46, a53 offset:2448
	ds_write_b32 v45, a38 offset:2720
	ds_write_b32 v46, a54 offset:2720
	ds_write_b32 v49, a39
	ds_write_b32 v50, a55
	ds_write_b32 v45, a40 offset:4352
	ds_write_b32 v46, a56 offset:4352
	ds_write_b32 v45, a41 offset:4624
	ds_write_b32 v46, a57 offset:4624
	ds_write_b32 v45, a42 offset:4896
	ds_write_b32 v46, a58 offset:4896
	ds_write_b32 v51, a43
	ds_write_b32 v52, a59
	ds_write_b32 v45, a44 offset:6528
	ds_write_b32 v46, a60 offset:6528
	ds_write_b32 v45, a45 offset:6800
	ds_write_b32 v46, a61 offset:6800
	ds_write_b32 v45, a46 offset:7072
	ds_write_b32 v46, a62 offset:7072
	ds_write_b32 v53, a47
	ds_write_b32 v54, a63
	v_or_b32_e32 v13, 64, v12
	ds_read_b128 v[2:5], v58
	ds_read_b128 v[6:9], v58 offset:16
	v_or_b32_e32 v10, v13, v44
	v_ashrrev_i32_e32 v11, 31, v10
	v_lshlrev_b64 v[10:11], 12, v[10:11]
	v_lshl_add_u64 v[10:11], v[0:1], 0, v[10:11]
	s_waitcnt lgkmcnt(1)
	global_store_dwordx4 v[10:11], v[2:5], off
	s_waitcnt lgkmcnt(0)
	global_store_dwordx4 v[10:11], v[6:9], off offset:16
	ds_read_b128 v[2:5], v58 offset:2176
	ds_read_b128 v[6:9], v58 offset:2192
	v_or_b32_e32 v10, v13, v55
	v_ashrrev_i32_e32 v11, 31, v10
	v_lshlrev_b64 v[10:11], 12, v[10:11]
	v_lshl_add_u64 v[10:11], v[0:1], 0, v[10:11]
	s_waitcnt lgkmcnt(1)
	global_store_dwordx4 v[10:11], v[2:5], off
	s_waitcnt lgkmcnt(0)
	global_store_dwordx4 v[10:11], v[6:9], off offset:16
	ds_read_b128 v[2:5], v58 offset:4352
	ds_read_b128 v[6:9], v58 offset:4368
	v_or_b32_e32 v10, v13, v56
	v_ashrrev_i32_e32 v11, 31, v10
	v_lshlrev_b64 v[10:11], 12, v[10:11]
	v_lshl_add_u64 v[10:11], v[0:1], 0, v[10:11]
	s_waitcnt lgkmcnt(1)
	global_store_dwordx4 v[10:11], v[2:5], off
	s_waitcnt lgkmcnt(0)
	global_store_dwordx4 v[10:11], v[6:9], off offset:16
	ds_read_b128 v[2:5], v58 offset:6528
	ds_read_b128 v[6:9], v58 offset:6544
	v_or_b32_e32 v10, v13, v57
	v_ashrrev_i32_e32 v11, 31, v10
	v_lshlrev_b64 v[10:11], 12, v[10:11]
	v_lshl_add_u64 v[10:11], v[0:1], 0, v[10:11]
	s_waitcnt lgkmcnt(1)
	global_store_dwordx4 v[10:11], v[2:5], off
	s_waitcnt lgkmcnt(0)
	global_store_dwordx4 v[10:11], v[6:9], off offset:16
	ds_write_b32 v45, a0
	ds_write_b32 v46, a16
	ds_write_b32 v45, a1 offset:272
	ds_write_b32 v46, a17 offset:272
	ds_write_b32 v45, a2 offset:544
	ds_write_b32 v46, a18 offset:544
	ds_write_b32 v47, a3
	ds_write_b32 v48, a19
	ds_write_b32 v45, a4 offset:2176
	ds_write_b32 v46, a20 offset:2176
	ds_write_b32 v45, a5 offset:2448
	ds_write_b32 v46, a21 offset:2448
	ds_write_b32 v45, a6 offset:2720
	ds_write_b32 v46, a22 offset:2720
	ds_write_b32 v49, a7
	ds_write_b32 v50, a23
	ds_write_b32 v45, a8 offset:4352
	ds_write_b32 v46, a24 offset:4352
	ds_write_b32 v45, a9 offset:4624
	ds_write_b32 v46, a25 offset:4624
	ds_write_b32 v45, a10 offset:4896
	ds_write_b32 v46, a26 offset:4896
	ds_write_b32 v51, a11
	ds_write_b32 v52, a27
	ds_write_b32 v45, a12 offset:6528
	ds_write_b32 v46, a28 offset:6528
	ds_write_b32 v45, a13 offset:6800
	ds_write_b32 v46, a29 offset:6800
	ds_write_b32 v45, a14 offset:7072
	ds_write_b32 v46, a30 offset:7072
	ds_write_b32 v53, a15
	ds_write_b32 v54, a31
	v_or_b32_e32 v12, 0x60, v12
	ds_read_b128 v[2:5], v58
	ds_read_b128 v[6:9], v58 offset:16
	v_or_b32_e32 v10, v12, v44
	v_ashrrev_i32_e32 v11, 31, v10
	v_lshlrev_b64 v[10:11], 12, v[10:11]
	v_lshl_add_u64 v[10:11], v[0:1], 0, v[10:11]
	s_waitcnt lgkmcnt(1)
	global_store_dwordx4 v[10:11], v[2:5], off
	s_waitcnt lgkmcnt(0)
	global_store_dwordx4 v[10:11], v[6:9], off offset:16
	ds_read_b128 v[2:5], v58 offset:2176
	ds_read_b128 v[6:9], v58 offset:2192
	v_or_b32_e32 v10, v12, v55
	v_ashrrev_i32_e32 v11, 31, v10
	v_lshlrev_b64 v[10:11], 12, v[10:11]
	v_lshl_add_u64 v[10:11], v[0:1], 0, v[10:11]
	s_waitcnt lgkmcnt(1)
	global_store_dwordx4 v[10:11], v[2:5], off
	s_waitcnt lgkmcnt(0)
	global_store_dwordx4 v[10:11], v[6:9], off offset:16
	ds_read_b128 v[2:5], v58 offset:4352
	ds_read_b128 v[6:9], v58 offset:4368
	v_or_b32_e32 v10, v12, v56
	v_ashrrev_i32_e32 v11, 31, v10
	v_lshlrev_b64 v[10:11], 12, v[10:11]
	v_lshl_add_u64 v[10:11], v[0:1], 0, v[10:11]
	s_waitcnt lgkmcnt(1)
	global_store_dwordx4 v[10:11], v[2:5], off
	s_waitcnt lgkmcnt(0)
	global_store_dwordx4 v[10:11], v[6:9], off offset:16
	ds_read_b128 v[2:5], v58 offset:6528
	ds_read_b128 v[6:9], v58 offset:6544
	v_or_b32_e32 v10, v12, v57
	v_ashrrev_i32_e32 v11, 31, v10
	v_lshlrev_b64 v[10:11], 12, v[10:11]
	v_lshl_add_u64 v[0:1], v[0:1], 0, v[10:11]
	s_waitcnt lgkmcnt(1)
	global_store_dwordx4 v[0:1], v[2:5], off
	s_waitcnt lgkmcnt(0)
	global_store_dwordx4 v[0:1], v[6:9], off offset:16
	s_branch .LBB0_43

.LBB0_68:
	v_add_u32_e32 v179, v176, v177
	ds_read_b128 v[84:87], v179
	ds_read_b128 v[108:111], v179 offset:32
	ds_read_b128 v[118:121], v179 offset:4608
	ds_read_b128 v[166:169], v179 offset:4640
	ds_read_b128 v[170:173], v179 offset:9216
	ds_read_b128 v[122:125], v179 offset:9248
	ds_read_b128 v[126:129], v179 offset:13824
	ds_read_b128 v[130:133], v179 offset:13856
	v_add_u32_e32 v88, v176, v178
	ds_read_b128 v[134:137], v88 offset:36864
	ds_read_b128 v[138:141], v88 offset:36896
	ds_read_b128 v[142:145], v88 offset:41472
	ds_read_b128 v[146:149], v88 offset:41504
	s_add_i32 s3, s3, 2
	s_sub_i32 s9, s8, 64
	s_cmp_lt_u32 s3, 5
	s_cselect_b32 s90, s9, 0
	s_lshl_b64 s[12:13], s[90:91], 1
	v_lshl_add_u64 v[42:43], v[64:65], 0, s[12:13]
	v_lshl_add_u64 v[112:113], v[66:67], 0, s[12:13]
	s_waitcnt lgkmcnt(3)
	v_mfma_f32_32x32x16_f16 a[96:111], v[84:87], v[134:137], a[96:111]
	s_waitcnt lgkmcnt(1)
	v_mfma_f32_32x32x16_f16 a[112:127], v[84:87], v[142:145], a[112:127]
	s_waitcnt vmcnt(23)
	ds_write_b128 v117, v[184:187] offset:55296
	v_lshl_add_u64 v[84:85], v[42:43], 0, v[68:69]
	v_lshl_add_u64 v[86:87], v[42:43], 0, v[70:71]
	v_mfma_f32_32x32x16_f16 a[64:79], v[118:121], v[134:137], a[64:79]
	global_load_dwordx4 v[184:187], v[84:85], off
	v_lshl_add_u64 v[84:85], v[112:113], 0, v[72:73]
	v_mfma_f32_32x32x16_f16 a[80:95], v[118:121], v[142:145], a[80:95]
	s_waitcnt vmcnt(23)
	ds_write_b128 v117, v[188:191] offset:59904
	global_load_dwordx4 v[188:191], v[86:87], off
	v_mfma_f32_32x32x16_f16 a[32:47], v[170:173], v[134:137], a[32:47]
	ds_read_b128 v[118:121], v179 offset:4672
	v_mfma_f32_32x32x16_f16 a[48:63], v[170:173], v[142:145], a[48:63]
	s_waitcnt vmcnt(17)
	ds_write_b128 v40, v[216:219]
	global_load_dwordx4 v[216:219], v[84:85], off
	v_mfma_f32_32x32x16_f16 a[0:15], v[126:129], v[134:137], a[0:15]
	ds_read_b128 v[84:87], v179 offset:64
	ds_read_b128 v[134:137], v179 offset:13888
	ds_read_b128 v[170:173], v88 offset:41536
	v_mfma_f32_32x32x16_f16 a[16:31], v[126:129], v[142:145], a[16:31]
	ds_read_b128 v[126:129], v179 offset:9280
	ds_read_b128 v[142:145], v88 offset:36928
	v_mfma_f32_32x32x16_f16 a[96:111], v[108:111], v[138:141], a[96:111]
	ds_write_b128 v117, v[192:195] offset:64512
	s_waitcnt lgkmcnt(10)
	v_mfma_f32_32x32x16_f16 a[112:127], v[108:111], v[146:149], a[112:127]
	v_lshl_add_u64 v[108:109], v[42:43], 0, v[74:75]
	v_lshl_add_u64 v[110:111], v[42:43], 0, v[76:77]
	global_load_dwordx4 v[192:195], v[108:109], off
	v_mfma_f32_32x32x16_f16 a[64:79], v[166:169], v[138:141], a[64:79]
	ds_write_b128 v174, v[196:199] offset:55296
	global_load_dwordx4 v[196:199], v[110:111], off
	v_mfma_f32_32x32x16_f16 a[80:95], v[166:169], v[146:149], a[80:95]
	v_lshl_add_u64 v[108:109], v[112:113], 0, v[78:79]
	ds_read_b128 v[166:169], v88 offset:41568
	v_mfma_f32_32x32x16_f16 a[32:47], v[122:125], v[138:141], a[32:47]
	s_waitcnt vmcnt(19)
	ds_write_b128 v40, v[220:223] offset:4608
	global_load_dwordx4 v[220:223], v[108:109], off
	v_mfma_f32_32x32x16_f16 a[48:63], v[122:125], v[146:149], a[48:63]
	ds_read_b128 v[108:111], v179 offset:96
	ds_read_b128 v[122:125], v179 offset:4704
	v_mfma_f32_32x32x16_f16 a[0:15], v[130:133], v[138:141], a[0:15]
	ds_read_b128 v[138:141], v179 offset:13920
	v_mfma_f32_32x32x16_f16 a[16:31], v[130:133], v[146:149], a[16:31]
	ds_read_b128 v[130:133], v179 offset:9312
	ds_read_b128 v[146:149], v88 offset:36960
	ds_write_b128 v174, v[200:203] offset:59904
	s_waitcnt lgkmcnt(10)
	v_mfma_f32_32x32x16_f16 a[96:111], v[84:87], v[142:145], a[96:111]
	v_mfma_f32_32x32x16_f16 a[112:127], v[84:87], v[170:173], a[112:127]
	ds_write_b128 v174, v[204:207] offset:64512
	v_lshl_add_u64 v[84:85], v[42:43], 0, v[152:153]
	v_lshl_add_u64 v[86:87], v[42:43], 0, v[154:155]
	v_mfma_f32_32x32x16_f16 a[64:79], v[118:121], v[142:145], a[64:79]
	global_load_dwordx4 v[200:203], v[84:85], off
	global_load_dwordx4 v[204:207], v[86:87], off
	v_mfma_f32_32x32x16_f16 a[80:95], v[118:121], v[170:173], a[80:95]
	v_lshl_add_u64 v[84:85], v[112:113], 0, v[156:157]
	s_waitcnt vmcnt(21)
	ds_write_b128 v40, v[224:227] offset:9216
	global_load_dwordx4 v[224:227], v[84:85], off
	v_mfma_f32_32x32x16_f16 a[32:47], v[126:129], v[142:145], a[32:47]
	v_lshl_add_u64 v[84:85], v[42:43], 0, v[158:159]
	v_lshl_add_u64 v[42:43], v[42:43], 0, v[160:161]
	v_mfma_f32_32x32x16_f16 a[48:63], v[126:129], v[170:173], a[48:63]
	v_mfma_f32_32x32x16_f16 a[0:15], v[134:137], v[142:145], a[0:15]
	ds_write_b128 v175, v[208:211] offset:59904
	global_load_dwordx4 v[208:211], v[84:85], off
	v_mfma_f32_32x32x16_f16 a[16:31], v[134:137], v[170:173], a[16:31]
	s_waitcnt lgkmcnt(4)
	v_mfma_f32_32x32x16_f16 a[96:111], v[108:111], v[146:149], a[96:111]
	ds_write_b128 v175, v[212:215] offset:64512
	global_load_dwordx4 v[212:215], v[42:43], off
	v_mfma_f32_32x32x16_f16 a[112:127], v[108:111], v[166:169], a[112:127]
	v_lshl_add_u64 v[42:43], v[112:113], 0, v[162:163]
	v_mfma_f32_32x32x16_f16 a[64:79], v[122:125], v[146:149], a[64:79]
	s_waitcnt vmcnt(23)
	ds_write_b128 v40, v[228:231] offset:13824
	global_load_dwordx4 v[228:231], v[42:43], off
	v_mfma_f32_32x32x16_f16 a[80:95], v[122:125], v[166:169], a[80:95]
	v_mfma_f32_32x32x16_f16 a[32:47], v[130:133], v[146:149], a[32:47]
	v_mfma_f32_32x32x16_f16 a[48:63], v[130:133], v[166:169], a[48:63]
	v_mfma_f32_32x32x16_f16 a[0:15], v[138:141], v[146:149], a[0:15]
	v_mfma_f32_32x32x16_f16 a[16:31], v[138:141], v[166:169], a[16:31]
	s_waitcnt lgkmcnt(0)
	s_barrier
	ds_read_b128 v[84:87], v179 offset:55296
	ds_read_b128 v[108:111], v179 offset:55328
	ds_read_b128 v[118:121], v179 offset:59904
	ds_read_b128 v[122:125], v179 offset:59936
	ds_read_b128 v[126:129], v179 offset:64512
	ds_read_b128 v[130:133], v179 offset:64544
	ds_read_b128 v[134:137], v164 offset:55296
	ds_read_b128 v[138:141], v164 offset:55328
	ds_read_b128 v[142:145], v165
	ds_read_b128 v[146:149], v165 offset:32
	ds_read_b128 v[166:169], v165 offset:4608
	ds_read_b128 v[170:173], v165 offset:4640
	s_cmp_lt_u32 s3, 4
	s_cselect_b32 s90, s8, 0
	s_lshl_b64 s[12:13], s[90:91], 1
	v_lshl_add_u64 v[42:43], v[64:65], 0, s[12:13]
	v_lshl_add_u64 v[112:113], v[66:67], 0, s[12:13]
	s_waitcnt lgkmcnt(3)
	v_mfma_f32_32x32x16_f16 a[96:111], v[84:87], v[142:145], a[96:111]
	s_waitcnt lgkmcnt(1)
	v_mfma_f32_32x32x16_f16 a[112:127], v[84:87], v[166:169], a[112:127]
	s_waitcnt vmcnt(23)
	ds_write_b128 v117, v[232:235]
	v_lshl_add_u64 v[84:85], v[42:43], 0, v[68:69]
	v_lshl_add_u64 v[86:87], v[42:43], 0, v[70:71]
	v_mfma_f32_32x32x16_f16 a[64:79], v[118:121], v[142:145], a[64:79]
	global_load_dwordx4 v[232:235], v[84:85], off
	v_lshl_add_u64 v[84:85], v[112:113], 0, v[72:73]
	v_mfma_f32_32x32x16_f16 a[80:95], v[118:121], v[166:169], a[80:95]
	s_waitcnt vmcnt(23)
	ds_write_b128 v117, v[236:239] offset:4608
	global_load_dwordx4 v[236:239], v[86:87], off
	v_mfma_f32_32x32x16_f16 a[32:47], v[126:129], v[142:145], a[32:47]
	ds_read_b128 v[118:121], v179 offset:59968
	v_mfma_f32_32x32x16_f16 a[48:63], v[126:129], v[166:169], a[48:63]
	s_waitcnt vmcnt(19)
	ds_write_b128 v117, a[140:143] offset:36864
	global_load_dwordx4 a[140:143], v[84:85], off
	v_mfma_f32_32x32x16_f16 a[0:15], v[134:137], v[142:145], a[0:15]
	ds_read_b128 v[84:87], v179 offset:55360
	ds_read_b128 v[126:129], v179 offset:64576
	ds_read_b128 v[142:145], v165 offset:64
	v_mfma_f32_32x32x16_f16 a[16:31], v[134:137], v[166:169], a[16:31]
	ds_read_b128 v[134:137], v164 offset:55360
	ds_read_b128 v[166:169], v165 offset:4672
	v_mfma_f32_32x32x16_f16 a[96:111], v[108:111], v[146:149], a[96:111]
	ds_write_b128 v117, v[240:243] offset:9216
	s_waitcnt lgkmcnt(10)
	v_mfma_f32_32x32x16_f16 a[112:127], v[108:111], v[170:173], a[112:127]
	v_lshl_add_u64 v[108:109], v[42:43], 0, v[74:75]
	v_lshl_add_u64 v[110:111], v[42:43], 0, v[76:77]
	global_load_dwordx4 v[240:243], v[108:109], off
	v_mfma_f32_32x32x16_f16 a[64:79], v[122:125], v[146:149], a[64:79]
	ds_write_b128 v117, v[244:247] offset:13824
	global_load_dwordx4 v[244:247], v[110:111], off
	v_mfma_f32_32x32x16_f16 a[80:95], v[122:125], v[170:173], a[80:95]
	v_lshl_add_u64 v[108:109], v[112:113], 0, v[78:79]
	ds_read_b128 v[122:125], v179 offset:60000
	v_mfma_f32_32x32x16_f16 a[32:47], v[130:133], v[146:149], a[32:47]
	s_waitcnt vmcnt(20)
	ds_write_b128 v117, a[144:147] offset:41472
	global_load_dwordx4 a[144:147], v[108:109], off
	v_mfma_f32_32x32x16_f16 a[48:63], v[130:133], v[170:173], a[48:63]
	ds_read_b128 v[108:111], v179 offset:55392
	ds_read_b128 v[130:133], v179 offset:64608
	v_mfma_f32_32x32x16_f16 a[0:15], v[138:141], v[146:149], a[0:15]
	ds_read_b128 v[146:149], v165 offset:96
	v_mfma_f32_32x32x16_f16 a[16:31], v[138:141], v[170:173], a[16:31]
	ds_read_b128 v[138:141], v164 offset:55392
	ds_read_b128 v[170:173], v165 offset:4704
	ds_write_b128 v117, v[248:251] offset:18432
	s_waitcnt lgkmcnt(12)
	v_mfma_f32_32x32x16_f16 a[96:111], v[84:87], v[142:145], a[96:111]
	s_waitcnt lgkmcnt(10)
	v_mfma_f32_32x32x16_f16 a[112:127], v[84:87], v[166:169], a[112:127]
	ds_write_b128 v117, a[128:131] offset:23040
	v_lshl_add_u64 v[84:85], v[42:43], 0, v[152:153]
	v_lshl_add_u64 v[86:87], v[42:43], 0, v[154:155]
	v_mfma_f32_32x32x16_f16 a[64:79], v[118:121], v[142:145], a[64:79]
	global_load_dwordx4 v[248:251], v[84:85], off
	global_load_dwordx4 a[128:131], v[86:87], off
	v_mfma_f32_32x32x16_f16 a[80:95], v[118:121], v[166:169], a[80:95]
	v_lshl_add_u64 v[84:85], v[112:113], 0, v[156:157]
	s_waitcnt vmcnt(21)
	ds_write_b128 v117, a[148:151] offset:46080
	global_load_dwordx4 a[148:151], v[84:85], off
	v_mfma_f32_32x32x16_f16 a[32:47], v[126:129], v[142:145], a[32:47]
	v_lshl_add_u64 v[84:85], v[42:43], 0, v[158:159]
	v_lshl_add_u64 v[42:43], v[42:43], 0, v[160:161]
	v_mfma_f32_32x32x16_f16 a[48:63], v[126:129], v[166:169], a[48:63]
	v_mfma_f32_32x32x16_f16 a[0:15], v[134:137], v[142:145], a[0:15]
	ds_write_b128 v117, a[132:135] offset:27648
	global_load_dwordx4 a[132:135], v[84:85], off
	v_mfma_f32_32x32x16_f16 a[16:31], v[134:137], v[166:169], a[16:31]
	s_waitcnt lgkmcnt(6)
	v_mfma_f32_32x32x16_f16 a[96:111], v[108:111], v[146:149], a[96:111]
	ds_write_b128 v117, a[136:139] offset:32256
	global_load_dwordx4 a[136:139], v[42:43], off
	s_waitcnt lgkmcnt(5)
	v_mfma_f32_32x32x16_f16 a[112:127], v[108:111], v[170:173], a[112:127]
	v_lshl_add_u64 v[42:43], v[112:113], 0, v[162:163]
	v_mfma_f32_32x32x16_f16 a[64:79], v[122:125], v[146:149], a[64:79]
	s_waitcnt vmcnt(23)
	ds_write_b128 v117, a[152:155] offset:50688
	global_load_dwordx4 a[152:155], v[42:43], off
	v_mfma_f32_32x32x16_f16 a[80:95], v[122:125], v[170:173], a[80:95]
	v_mfma_f32_32x32x16_f16 a[32:47], v[130:133], v[146:149], a[32:47]
	v_mfma_f32_32x32x16_f16 a[48:63], v[130:133], v[170:173], a[48:63]
	v_mfma_f32_32x32x16_f16 a[0:15], v[138:141], v[146:149], a[0:15]
	v_mfma_f32_32x32x16_f16 a[16:31], v[138:141], v[170:173], a[16:31]
	s_waitcnt lgkmcnt(0)
	s_barrier
	s_addk_i32 s8, 0x80
	s_cmp_lt_u32 s3, 6
	s_cbranch_scc1 .LBB0_68
	v_accvgpr_read_b32 v42, a176
	s_lshl_b32 s90, s2, 11
	v_accvgpr_read_b32 v43, a177
	v_lshl_add_u64 v[42:43], v[42:43], 0, s[90:91]
	global_load_dwordx4 v[76:79], v[42:43], off
	v_accvgpr_read_b32 v42, a178
	v_accvgpr_read_b32 v43, a179
	v_lshl_add_u64 v[42:43], v[42:43], 0, s[90:91]
	global_load_dwordx4 v[72:75], v[42:43], off
	v_accvgpr_read_b32 v42, a180
	v_accvgpr_read_b32 v43, a181
	v_lshl_add_u64 v[42:43], v[42:43], 0, s[90:91]
	global_load_dwordx4 v[68:71], v[42:43], off
	v_accvgpr_read_b32 v42, a182
	v_accvgpr_read_b32 v43, a183
	v_lshl_add_u64 v[42:43], v[42:43], 0, s[90:91]
	global_load_dwordx4 v[64:67], v[42:43], off
	ds_write_b32 v89, a96
	ds_write_b32 v91, a112
	ds_write_b32 v89, a97 offset:272
	ds_write_b32 v91, a113 offset:272
	ds_write_b32 v89, a98 offset:544
	ds_write_b32 v91, a114 offset:544
	ds_write_b32 v93, a99
	ds_write_b32 v95, a115
	ds_write_b32 v89, a100 offset:2176
	ds_write_b32 v91, a116 offset:2176
	ds_write_b32 v89, a101 offset:2448
	ds_write_b32 v91, a117 offset:2448
	ds_write_b32 v89, a102 offset:2720
	ds_write_b32 v91, a118 offset:2720
	ds_write_b32 v97, a103
	ds_write_b32 v99, a119
	ds_write_b32 v89, a104 offset:4352
	ds_write_b32 v91, a120 offset:4352
	ds_write_b32 v89, a105 offset:4624
	ds_write_b32 v91, a121 offset:4624
	ds_write_b32 v89, a106 offset:4896
	ds_write_b32 v91, a122 offset:4896
	ds_write_b32 v101, a107
	ds_write_b32 v103, a123
	ds_write_b32 v89, a108 offset:6528
	ds_write_b32 v91, a124 offset:6528
	ds_write_b32 v89, a109 offset:6800
	ds_write_b32 v91, a125 offset:6800
	ds_write_b32 v89, a110 offset:7072
	ds_write_b32 v91, a126 offset:7072
	ds_write_b32 v105, a111
	ds_write_b32 v107, a127
	ds_read_b128 v[84:87], v115
	ds_read_b128 v[108:111], v115 offset:16
	v_cvt_f32_f16_sdwa v43, v60 dst_sel:DWORD dst_unused:UNUSED_PAD src0_sel:WORD_1
	v_cvt_f32_f16_e32 v42, v60
	s_add_i32 s2, s2, 1
	s_cmp_eq_u32 s2, 3
	s_waitcnt vmcnt(3)
	v_cvt_f32_f16_e32 v112, v76
	v_cvt_f32_f16_sdwa v113, v76 dst_sel:DWORD dst_unused:UNUSED_PAD src0_sel:WORD_1
	v_cvt_f32_f16_e32 v76, v77
	v_cvt_f32_f16_sdwa v77, v77 dst_sel:DWORD dst_unused:UNUSED_PAD src0_sel:WORD_1
	s_waitcnt lgkmcnt(1)
	v_pk_fma_f32 v[42:43], v[84:85], v[112:113], v[42:43]
	s_nop 0
	v_cvt_pk_f16_f32 v60, v42, v43
	v_cvt_f32_f16_sdwa v43, v61 dst_sel:DWORD dst_unused:UNUSED_PAD src0_sel:WORD_1
	v_cvt_f32_f16_e32 v42, v61
	v_pk_fma_f32 v[42:43], v[86:87], v[76:77], v[42:43]
	s_nop 0
	v_cvt_pk_f16_f32 v61, v42, v43
	v_cvt_f32_f16_sdwa v43, v62 dst_sel:DWORD dst_unused:UNUSED_PAD src0_sel:WORD_1
	v_cvt_f32_f16_e32 v42, v62
	v_cvt_f32_f16_e32 v76, v78
	v_cvt_f32_f16_sdwa v77, v78 dst_sel:DWORD dst_unused:UNUSED_PAD src0_sel:WORD_1
	s_waitcnt lgkmcnt(0)
	v_pk_fma_f32 v[42:43], v[108:109], v[76:77], v[42:43]
	s_nop 0
	v_cvt_pk_f16_f32 v62, v42, v43
	v_cvt_f32_f16_sdwa v43, v63 dst_sel:DWORD dst_unused:UNUSED_PAD src0_sel:WORD_1
	v_cvt_f32_f16_e32 v42, v63
	v_cvt_f32_f16_e32 v76, v79
	v_cvt_f32_f16_sdwa v77, v79 dst_sel:DWORD dst_unused:UNUSED_PAD src0_sel:WORD_1
	s_waitcnt vmcnt(2)
	v_cvt_f32_f16_e32 v108, v72
	v_cvt_f32_f16_sdwa v109, v72 dst_sel:DWORD dst_unused:UNUSED_PAD src0_sel:WORD_1
	v_cvt_f32_f16_e32 v72, v73
	v_pk_fma_f32 v[42:43], v[110:111], v[76:77], v[42:43]
	ds_read_b128 v[76:79], v115 offset:2176
	ds_read_b128 v[84:87], v115 offset:2192
	v_cvt_pk_f16_f32 v63, v42, v43
	v_cvt_f32_f16_sdwa v43, v56 dst_sel:DWORD dst_unused:UNUSED_PAD src0_sel:WORD_1
	v_cvt_f32_f16_e32 v42, v56
	v_cvt_f32_f16_sdwa v73, v73 dst_sel:DWORD dst_unused:UNUSED_PAD src0_sel:WORD_1
	s_waitcnt lgkmcnt(1)
	v_pk_fma_f32 v[42:43], v[76:77], v[108:109], v[42:43]
	s_nop 0
	v_cvt_pk_f16_f32 v56, v42, v43
	v_cvt_f32_f16_sdwa v43, v57 dst_sel:DWORD dst_unused:UNUSED_PAD src0_sel:WORD_1
	v_cvt_f32_f16_e32 v42, v57
	v_pk_fma_f32 v[42:43], v[78:79], v[72:73], v[42:43]
	s_nop 0
	v_cvt_pk_f16_f32 v57, v42, v43
	v_cvt_f32_f16_sdwa v43, v58 dst_sel:DWORD dst_unused:UNUSED_PAD src0_sel:WORD_1
	v_cvt_f32_f16_e32 v42, v58
	v_cvt_f32_f16_e32 v72, v74
	v_cvt_f32_f16_sdwa v73, v74 dst_sel:DWORD dst_unused:UNUSED_PAD src0_sel:WORD_1
	s_waitcnt lgkmcnt(0)
	v_pk_fma_f32 v[42:43], v[84:85], v[72:73], v[42:43]
	s_nop 0
	v_cvt_pk_f16_f32 v58, v42, v43
	v_cvt_f32_f16_sdwa v43, v59 dst_sel:DWORD dst_unused:UNUSED_PAD src0_sel:WORD_1
	v_cvt_f32_f16_e32 v42, v59
	v_cvt_f32_f16_e32 v72, v75
	v_cvt_f32_f16_sdwa v73, v75 dst_sel:DWORD dst_unused:UNUSED_PAD src0_sel:WORD_1
	s_waitcnt vmcnt(1)
	v_cvt_f32_f16_e32 v84, v68
	v_cvt_f32_f16_sdwa v85, v68 dst_sel:DWORD dst_unused:UNUSED_PAD src0_sel:WORD_1
	v_cvt_f32_f16_e32 v68, v69
	v_pk_fma_f32 v[42:43], v[86:87], v[72:73], v[42:43]
	ds_read_b128 v[72:75], v115 offset:4352
	ds_read_b128 v[76:79], v115 offset:4368
	v_cvt_pk_f16_f32 v59, v42, v43
	v_cvt_f32_f16_sdwa v43, v52 dst_sel:DWORD dst_unused:UNUSED_PAD src0_sel:WORD_1
	v_cvt_f32_f16_e32 v42, v52
	v_cvt_f32_f16_sdwa v69, v69 dst_sel:DWORD dst_unused:UNUSED_PAD src0_sel:WORD_1
	s_waitcnt lgkmcnt(1)
	v_pk_fma_f32 v[42:43], v[72:73], v[84:85], v[42:43]
	s_nop 0
	v_cvt_pk_f16_f32 v52, v42, v43
	v_cvt_f32_f16_sdwa v43, v53 dst_sel:DWORD dst_unused:UNUSED_PAD src0_sel:WORD_1
	v_cvt_f32_f16_e32 v42, v53
	v_pk_fma_f32 v[42:43], v[74:75], v[68:69], v[42:43]
	s_nop 0
	v_cvt_pk_f16_f32 v53, v42, v43
	v_cvt_f32_f16_sdwa v43, v54 dst_sel:DWORD dst_unused:UNUSED_PAD src0_sel:WORD_1
	v_cvt_f32_f16_e32 v42, v54
	v_cvt_f32_f16_e32 v68, v70
	v_cvt_f32_f16_sdwa v69, v70 dst_sel:DWORD dst_unused:UNUSED_PAD src0_sel:WORD_1
	s_waitcnt lgkmcnt(0)
	v_pk_fma_f32 v[42:43], v[76:77], v[68:69], v[42:43]
	s_nop 0
	v_cvt_pk_f16_f32 v54, v42, v43
	v_cvt_f32_f16_sdwa v43, v55 dst_sel:DWORD dst_unused:UNUSED_PAD src0_sel:WORD_1
	v_cvt_f32_f16_e32 v42, v55
	v_cvt_f32_f16_e32 v68, v71
	v_cvt_f32_f16_sdwa v69, v71 dst_sel:DWORD dst_unused:UNUSED_PAD src0_sel:WORD_1
	s_waitcnt vmcnt(0)
	v_cvt_f32_f16_e32 v76, v64
	v_cvt_f32_f16_sdwa v77, v64 dst_sel:DWORD dst_unused:UNUSED_PAD src0_sel:WORD_1
	v_cvt_f32_f16_e32 v64, v65
	v_pk_fma_f32 v[42:43], v[78:79], v[68:69], v[42:43]
	ds_read_b128 v[68:71], v115 offset:6528
	ds_read_b128 v[72:75], v115 offset:6544
	v_cvt_pk_f16_f32 v55, v42, v43
	v_cvt_f32_f16_sdwa v43, v48 dst_sel:DWORD dst_unused:UNUSED_PAD src0_sel:WORD_1
	v_cvt_f32_f16_e32 v42, v48
	v_cvt_f32_f16_sdwa v65, v65 dst_sel:DWORD dst_unused:UNUSED_PAD src0_sel:WORD_1
	s_waitcnt lgkmcnt(1)
	v_pk_fma_f32 v[42:43], v[68:69], v[76:77], v[42:43]
	s_nop 0
	v_cvt_pk_f16_f32 v48, v42, v43
	v_cvt_f32_f16_sdwa v43, v49 dst_sel:DWORD dst_unused:UNUSED_PAD src0_sel:WORD_1
	v_cvt_f32_f16_e32 v42, v49
	v_pk_fma_f32 v[42:43], v[70:71], v[64:65], v[42:43]
	s_nop 0
	v_cvt_pk_f16_f32 v49, v42, v43
	v_cvt_f32_f16_sdwa v43, v50 dst_sel:DWORD dst_unused:UNUSED_PAD src0_sel:WORD_1
	v_cvt_f32_f16_e32 v42, v50
	v_cvt_f32_f16_e32 v64, v66
	v_cvt_f32_f16_sdwa v65, v66 dst_sel:DWORD dst_unused:UNUSED_PAD src0_sel:WORD_1
	s_waitcnt lgkmcnt(0)
	v_pk_fma_f32 v[42:43], v[72:73], v[64:65], v[42:43]
	s_nop 0
	v_cvt_pk_f16_f32 v50, v42, v43
	v_cvt_f32_f16_sdwa v43, v51 dst_sel:DWORD dst_unused:UNUSED_PAD src0_sel:WORD_1
	v_cvt_f32_f16_e32 v42, v51
	v_cvt_f32_f16_e32 v64, v67
	v_cvt_f32_f16_sdwa v65, v67 dst_sel:DWORD dst_unused:UNUSED_PAD src0_sel:WORD_1
	v_pk_fma_f32 v[42:43], v[74:75], v[64:65], v[42:43]
	s_nop 0
	v_cvt_pk_f16_f32 v51, v42, v43
	v_accvgpr_read_b32 v42, a184
	v_accvgpr_read_b32 v43, a185
	v_lshl_add_u64 v[42:43], v[42:43], 0, s[90:91]
	global_load_dwordx4 v[72:75], v[42:43], off
	v_accvgpr_read_b32 v42, a186
	v_accvgpr_read_b32 v43, a187
	v_lshl_add_u64 v[42:43], v[42:43], 0, s[90:91]
	global_load_dwordx4 v[76:79], v[42:43], off
	v_accvgpr_read_b32 v42, a188
	v_accvgpr_read_b32 v43, a189
	v_lshl_add_u64 v[42:43], v[42:43], 0, s[90:91]
	global_load_dwordx4 v[68:71], v[42:43], off
	v_accvgpr_read_b32 v42, a190
	v_accvgpr_read_b32 v43, a191
	v_lshl_add_u64 v[42:43], v[42:43], 0, s[90:91]
	global_load_dwordx4 v[64:67], v[42:43], off
	ds_write_b32 v89, a64
	ds_write_b32 v91, a80
	ds_write_b32 v89, a65 offset:272
	ds_write_b32 v91, a81 offset:272
	ds_write_b32 v89, a66 offset:544
	ds_write_b32 v91, a82 offset:544
	ds_write_b32 v93, a67
	ds_write_b32 v95, a83
	ds_write_b32 v89, a68 offset:2176
	ds_write_b32 v91, a84 offset:2176
	ds_write_b32 v89, a69 offset:2448
	ds_write_b32 v91, a85 offset:2448
	ds_write_b32 v89, a70 offset:2720
	ds_write_b32 v91, a86 offset:2720
	ds_write_b32 v97, a71
	ds_write_b32 v99, a87
	ds_write_b32 v89, a72 offset:4352
	ds_write_b32 v91, a88 offset:4352
	ds_write_b32 v89, a73 offset:4624
	ds_write_b32 v91, a89 offset:4624
	ds_write_b32 v89, a74 offset:4896
	ds_write_b32 v91, a90 offset:4896
	ds_write_b32 v101, a75
	ds_write_b32 v103, a91
	ds_write_b32 v89, a76 offset:6528
	ds_write_b32 v91, a92 offset:6528
	ds_write_b32 v89, a77 offset:6800
	ds_write_b32 v91, a93 offset:6800
	ds_write_b32 v89, a78 offset:7072
	ds_write_b32 v91, a94 offset:7072
	ds_write_b32 v105, a79
	ds_write_b32 v107, a95
	ds_read_b128 v[84:87], v115
	ds_read_b128 v[108:111], v115 offset:16
	v_cvt_f32_f16_sdwa v43, v44 dst_sel:DWORD dst_unused:UNUSED_PAD src0_sel:WORD_1
	v_cvt_f32_f16_e32 v42, v44
	s_waitcnt vmcnt(3)
	v_cvt_f32_f16_e32 v112, v72
	v_cvt_f32_f16_sdwa v113, v72 dst_sel:DWORD dst_unused:UNUSED_PAD src0_sel:WORD_1
	v_cvt_f32_f16_e32 v72, v73
	v_cvt_f32_f16_sdwa v73, v73 dst_sel:DWORD dst_unused:UNUSED_PAD src0_sel:WORD_1
	s_waitcnt lgkmcnt(1)
	v_pk_fma_f32 v[42:43], v[84:85], v[112:113], v[42:43]
	s_nop 0
	v_cvt_pk_f16_f32 v44, v42, v43
	v_cvt_f32_f16_sdwa v43, v45 dst_sel:DWORD dst_unused:UNUSED_PAD src0_sel:WORD_1
	v_cvt_f32_f16_e32 v42, v45
	v_pk_fma_f32 v[42:43], v[86:87], v[72:73], v[42:43]
	s_nop 0
	v_cvt_pk_f16_f32 v45, v42, v43
	v_cvt_f32_f16_sdwa v43, v46 dst_sel:DWORD dst_unused:UNUSED_PAD src0_sel:WORD_1
	v_cvt_f32_f16_e32 v42, v46
	v_cvt_f32_f16_e32 v72, v74
	v_cvt_f32_f16_sdwa v73, v74 dst_sel:DWORD dst_unused:UNUSED_PAD src0_sel:WORD_1
	s_waitcnt lgkmcnt(0)
	v_pk_fma_f32 v[42:43], v[108:109], v[72:73], v[42:43]
	s_nop 0
	v_cvt_pk_f16_f32 v46, v42, v43
	v_cvt_f32_f16_sdwa v43, v47 dst_sel:DWORD dst_unused:UNUSED_PAD src0_sel:WORD_1
	v_cvt_f32_f16_e32 v42, v47
	v_cvt_f32_f16_e32 v72, v75
	v_cvt_f32_f16_sdwa v73, v75 dst_sel:DWORD dst_unused:UNUSED_PAD src0_sel:WORD_1
	s_waitcnt vmcnt(2)
	v_cvt_f32_f16_e32 v108, v76
	v_cvt_f32_f16_sdwa v109, v76 dst_sel:DWORD dst_unused:UNUSED_PAD src0_sel:WORD_1
	v_pk_fma_f32 v[42:43], v[110:111], v[72:73], v[42:43]
	s_nop 0
	v_cvt_pk_f16_f32 v47, v42, v43
	ds_read_b128 v[72:75], v115 offset:2176
	ds_read_b128 v[84:87], v115 offset:2192
	v_cvt_f32_f16_sdwa v43, v180 dst_sel:DWORD dst_unused:UNUSED_PAD src0_sel:WORD_1
	v_cvt_f32_f16_e32 v42, v180
	s_waitcnt lgkmcnt(1)
	v_pk_fma_f32 v[42:43], v[72:73], v[108:109], v[42:43]
	s_nop 0
	v_cvt_pk_f16_f32 v180, v42, v43
	v_cvt_f32_f16_sdwa v43, v181 dst_sel:DWORD dst_unused:UNUSED_PAD src0_sel:WORD_1
	v_cvt_f32_f16_e32 v42, v181
	v_cvt_f32_f16_e32 v72, v77
	v_cvt_f32_f16_sdwa v73, v77 dst_sel:DWORD dst_unused:UNUSED_PAD src0_sel:WORD_1
	v_pk_fma_f32 v[42:43], v[74:75], v[72:73], v[42:43]
	s_nop 0
	v_cvt_pk_f16_f32 v181, v42, v43
	v_cvt_f32_f16_sdwa v43, v182 dst_sel:DWORD dst_unused:UNUSED_PAD src0_sel:WORD_1
	v_cvt_f32_f16_e32 v42, v182
	v_cvt_f32_f16_e32 v72, v78
	v_cvt_f32_f16_sdwa v73, v78 dst_sel:DWORD dst_unused:UNUSED_PAD src0_sel:WORD_1
	s_waitcnt lgkmcnt(0)
	v_pk_fma_f32 v[42:43], v[84:85], v[72:73], v[42:43]
	s_nop 0
	v_cvt_pk_f16_f32 v182, v42, v43
	v_cvt_f32_f16_sdwa v43, v183 dst_sel:DWORD dst_unused:UNUSED_PAD src0_sel:WORD_1
	v_cvt_f32_f16_e32 v42, v183
	v_cvt_f32_f16_e32 v72, v79
	v_cvt_f32_f16_sdwa v73, v79 dst_sel:DWORD dst_unused:UNUSED_PAD src0_sel:WORD_1
	s_waitcnt vmcnt(1)
	v_cvt_f32_f16_e32 v84, v68
	v_cvt_f32_f16_sdwa v85, v68 dst_sel:DWORD dst_unused:UNUSED_PAD src0_sel:WORD_1
	v_cvt_f32_f16_e32 v68, v69
	v_pk_fma_f32 v[42:43], v[86:87], v[72:73], v[42:43]
	ds_read_b128 v[72:75], v115 offset:4352
	ds_read_b128 v[76:79], v115 offset:4368
	v_cvt_pk_f16_f32 v183, v42, v43
	v_cvt_f32_f16_sdwa v43, v36 dst_sel:DWORD dst_unused:UNUSED_PAD src0_sel:WORD_1
	v_cvt_f32_f16_e32 v42, v36
	v_cvt_f32_f16_sdwa v69, v69 dst_sel:DWORD dst_unused:UNUSED_PAD src0_sel:WORD_1
	s_waitcnt lgkmcnt(1)
	v_pk_fma_f32 v[42:43], v[72:73], v[84:85], v[42:43]
	s_nop 0
	v_cvt_pk_f16_f32 v36, v42, v43
	v_cvt_f32_f16_sdwa v43, v37 dst_sel:DWORD dst_unused:UNUSED_PAD src0_sel:WORD_1
	v_cvt_f32_f16_e32 v42, v37
	v_pk_fma_f32 v[42:43], v[74:75], v[68:69], v[42:43]
	s_nop 0
	v_cvt_pk_f16_f32 v37, v42, v43
	v_cvt_f32_f16_sdwa v43, v38 dst_sel:DWORD dst_unused:UNUSED_PAD src0_sel:WORD_1
	v_cvt_f32_f16_e32 v42, v38
	v_cvt_f32_f16_e32 v68, v70
	v_cvt_f32_f16_sdwa v69, v70 dst_sel:DWORD dst_unused:UNUSED_PAD src0_sel:WORD_1
	s_waitcnt lgkmcnt(0)
	v_pk_fma_f32 v[42:43], v[76:77], v[68:69], v[42:43]
	s_nop 0
	v_cvt_pk_f16_f32 v38, v42, v43
	v_cvt_f32_f16_sdwa v43, v39 dst_sel:DWORD dst_unused:UNUSED_PAD src0_sel:WORD_1
	v_cvt_f32_f16_e32 v42, v39
	v_cvt_f32_f16_e32 v68, v71
	v_cvt_f32_f16_sdwa v69, v71 dst_sel:DWORD dst_unused:UNUSED_PAD src0_sel:WORD_1
	s_waitcnt vmcnt(0)
	v_cvt_f32_f16_e32 v76, v64
	v_cvt_f32_f16_sdwa v77, v64 dst_sel:DWORD dst_unused:UNUSED_PAD src0_sel:WORD_1
	v_cvt_f32_f16_e32 v64, v65
	v_pk_fma_f32 v[42:43], v[78:79], v[68:69], v[42:43]
	ds_read_b128 v[68:71], v115 offset:6528
	ds_read_b128 v[72:75], v115 offset:6544
	v_cvt_pk_f16_f32 v39, v42, v43
	v_cvt_f32_f16_sdwa v43, v32 dst_sel:DWORD dst_unused:UNUSED_PAD src0_sel:WORD_1
	v_cvt_f32_f16_e32 v42, v32
	v_cvt_f32_f16_sdwa v65, v65 dst_sel:DWORD dst_unused:UNUSED_PAD src0_sel:WORD_1
	s_waitcnt lgkmcnt(1)
	v_pk_fma_f32 v[42:43], v[68:69], v[76:77], v[42:43]
	s_nop 0
	v_cvt_pk_f16_f32 v32, v42, v43
	v_cvt_f32_f16_sdwa v43, v33 dst_sel:DWORD dst_unused:UNUSED_PAD src0_sel:WORD_1
	v_cvt_f32_f16_e32 v42, v33
	v_pk_fma_f32 v[42:43], v[70:71], v[64:65], v[42:43]
	s_nop 0
	v_cvt_pk_f16_f32 v33, v42, v43
	v_cvt_f32_f16_sdwa v43, v34 dst_sel:DWORD dst_unused:UNUSED_PAD src0_sel:WORD_1
	v_cvt_f32_f16_e32 v42, v34
	v_cvt_f32_f16_e32 v64, v66
	v_cvt_f32_f16_sdwa v65, v66 dst_sel:DWORD dst_unused:UNUSED_PAD src0_sel:WORD_1
	s_waitcnt lgkmcnt(0)
	v_pk_fma_f32 v[42:43], v[72:73], v[64:65], v[42:43]
	s_nop 0
	v_cvt_pk_f16_f32 v34, v42, v43
	v_cvt_f32_f16_sdwa v43, v35 dst_sel:DWORD dst_unused:UNUSED_PAD src0_sel:WORD_1
	v_cvt_f32_f16_e32 v42, v35
	v_cvt_f32_f16_e32 v64, v67
	v_cvt_f32_f16_sdwa v65, v67 dst_sel:DWORD dst_unused:UNUSED_PAD src0_sel:WORD_1
	v_pk_fma_f32 v[42:43], v[74:75], v[64:65], v[42:43]
	s_nop 0
	v_cvt_pk_f16_f32 v35, v42, v43
	v_accvgpr_read_b32 v42, a192
	v_accvgpr_read_b32 v43, a193
	v_lshl_add_u64 v[42:43], v[42:43], 0, s[90:91]
	global_load_dwordx4 v[72:75], v[42:43], off
	v_accvgpr_read_b32 v42, a194
	v_accvgpr_read_b32 v43, a195
	v_lshl_add_u64 v[42:43], v[42:43], 0, s[90:91]
	global_load_dwordx4 v[76:79], v[42:43], off
	v_accvgpr_read_b32 v42, a196
	v_accvgpr_read_b32 v43, a197
	v_lshl_add_u64 v[42:43], v[42:43], 0, s[90:91]
	global_load_dwordx4 v[68:71], v[42:43], off
	v_accvgpr_read_b32 v42, a198
	v_accvgpr_read_b32 v43, a199
	v_lshl_add_u64 v[42:43], v[42:43], 0, s[90:91]
	global_load_dwordx4 v[64:67], v[42:43], off
	ds_write_b32 v89, a32
	ds_write_b32 v91, a48
	ds_write_b32 v89, a33 offset:272
	ds_write_b32 v91, a49 offset:272
	ds_write_b32 v89, a34 offset:544
	ds_write_b32 v91, a50 offset:544
	ds_write_b32 v93, a35
	ds_write_b32 v95, a51
	ds_write_b32 v89, a36 offset:2176
	ds_write_b32 v91, a52 offset:2176
	ds_write_b32 v89, a37 offset:2448
	ds_write_b32 v91, a53 offset:2448
	ds_write_b32 v89, a38 offset:2720
	ds_write_b32 v91, a54 offset:2720
	ds_write_b32 v97, a39
	ds_write_b32 v99, a55
	ds_write_b32 v89, a40 offset:4352
	ds_write_b32 v91, a56 offset:4352
	ds_write_b32 v89, a41 offset:4624
	ds_write_b32 v91, a57 offset:4624
	ds_write_b32 v89, a42 offset:4896
	ds_write_b32 v91, a58 offset:4896
	ds_write_b32 v101, a43
	ds_write_b32 v103, a59
	ds_write_b32 v89, a44 offset:6528
	ds_write_b32 v91, a60 offset:6528
	ds_write_b32 v89, a45 offset:6800
	ds_write_b32 v91, a61 offset:6800
	ds_write_b32 v89, a46 offset:7072
	ds_write_b32 v91, a62 offset:7072
	ds_write_b32 v105, a47
	ds_write_b32 v107, a63
	ds_read_b128 v[84:87], v115
	ds_read_b128 v[108:111], v115 offset:16
	v_cvt_f32_f16_sdwa v43, v28 dst_sel:DWORD dst_unused:UNUSED_PAD src0_sel:WORD_1
	v_cvt_f32_f16_e32 v42, v28
	s_waitcnt vmcnt(3)
	v_cvt_f32_f16_e32 v112, v72
	v_cvt_f32_f16_sdwa v113, v72 dst_sel:DWORD dst_unused:UNUSED_PAD src0_sel:WORD_1
	v_cvt_f32_f16_e32 v72, v73
	v_cvt_f32_f16_sdwa v73, v73 dst_sel:DWORD dst_unused:UNUSED_PAD src0_sel:WORD_1
	s_waitcnt lgkmcnt(1)
	v_pk_fma_f32 v[42:43], v[84:85], v[112:113], v[42:43]
	s_nop 0
	v_cvt_pk_f16_f32 v28, v42, v43
	v_cvt_f32_f16_sdwa v43, v29 dst_sel:DWORD dst_unused:UNUSED_PAD src0_sel:WORD_1
	v_cvt_f32_f16_e32 v42, v29
	v_pk_fma_f32 v[42:43], v[86:87], v[72:73], v[42:43]
	s_nop 0
	v_cvt_pk_f16_f32 v29, v42, v43
	v_cvt_f32_f16_sdwa v43, v30 dst_sel:DWORD dst_unused:UNUSED_PAD src0_sel:WORD_1
	v_cvt_f32_f16_e32 v42, v30
	v_cvt_f32_f16_e32 v72, v74
	v_cvt_f32_f16_sdwa v73, v74 dst_sel:DWORD dst_unused:UNUSED_PAD src0_sel:WORD_1
	s_waitcnt lgkmcnt(0)
	v_pk_fma_f32 v[42:43], v[108:109], v[72:73], v[42:43]
	s_nop 0
	v_cvt_pk_f16_f32 v30, v42, v43
	v_cvt_f32_f16_sdwa v43, v31 dst_sel:DWORD dst_unused:UNUSED_PAD src0_sel:WORD_1
	v_cvt_f32_f16_e32 v42, v31
	v_cvt_f32_f16_e32 v72, v75
	v_cvt_f32_f16_sdwa v73, v75 dst_sel:DWORD dst_unused:UNUSED_PAD src0_sel:WORD_1
	s_waitcnt vmcnt(2)
	v_cvt_f32_f16_e32 v108, v76
	v_cvt_f32_f16_sdwa v109, v76 dst_sel:DWORD dst_unused:UNUSED_PAD src0_sel:WORD_1
	v_pk_fma_f32 v[42:43], v[110:111], v[72:73], v[42:43]
	s_nop 0
	v_cvt_pk_f16_f32 v31, v42, v43
	ds_read_b128 v[72:75], v115 offset:2176
	ds_read_b128 v[84:87], v115 offset:2192
	v_cvt_f32_f16_sdwa v43, v24 dst_sel:DWORD dst_unused:UNUSED_PAD src0_sel:WORD_1
	v_cvt_f32_f16_e32 v42, v24
	s_waitcnt lgkmcnt(1)
	v_pk_fma_f32 v[42:43], v[72:73], v[108:109], v[42:43]
	s_nop 0
	v_cvt_pk_f16_f32 v24, v42, v43
	v_cvt_f32_f16_sdwa v43, v25 dst_sel:DWORD dst_unused:UNUSED_PAD src0_sel:WORD_1
	v_cvt_f32_f16_e32 v42, v25
	v_cvt_f32_f16_e32 v72, v77
	v_cvt_f32_f16_sdwa v73, v77 dst_sel:DWORD dst_unused:UNUSED_PAD src0_sel:WORD_1
	v_pk_fma_f32 v[42:43], v[74:75], v[72:73], v[42:43]
	s_nop 0
	v_cvt_pk_f16_f32 v25, v42, v43
	v_cvt_f32_f16_sdwa v43, v26 dst_sel:DWORD dst_unused:UNUSED_PAD src0_sel:WORD_1
	v_cvt_f32_f16_e32 v42, v26
	v_cvt_f32_f16_e32 v72, v78
	v_cvt_f32_f16_sdwa v73, v78 dst_sel:DWORD dst_unused:UNUSED_PAD src0_sel:WORD_1
	s_waitcnt lgkmcnt(0)
	v_pk_fma_f32 v[42:43], v[84:85], v[72:73], v[42:43]
	s_nop 0
	v_cvt_pk_f16_f32 v26, v42, v43
	v_cvt_f32_f16_sdwa v43, v27 dst_sel:DWORD dst_unused:UNUSED_PAD src0_sel:WORD_1
	v_cvt_f32_f16_e32 v42, v27
	v_cvt_f32_f16_e32 v72, v79
	v_cvt_f32_f16_sdwa v73, v79 dst_sel:DWORD dst_unused:UNUSED_PAD src0_sel:WORD_1
	s_waitcnt vmcnt(1)
	v_cvt_f32_f16_e32 v84, v68
	v_cvt_f32_f16_sdwa v85, v68 dst_sel:DWORD dst_unused:UNUSED_PAD src0_sel:WORD_1
	v_cvt_f32_f16_e32 v68, v69
	v_pk_fma_f32 v[42:43], v[86:87], v[72:73], v[42:43]
	ds_read_b128 v[72:75], v115 offset:4352
	ds_read_b128 v[76:79], v115 offset:4368
	v_cvt_pk_f16_f32 v27, v42, v43
	v_cvt_f32_f16_sdwa v43, v20 dst_sel:DWORD dst_unused:UNUSED_PAD src0_sel:WORD_1
	v_cvt_f32_f16_e32 v42, v20
	v_cvt_f32_f16_sdwa v69, v69 dst_sel:DWORD dst_unused:UNUSED_PAD src0_sel:WORD_1
	s_waitcnt lgkmcnt(1)
	v_pk_fma_f32 v[42:43], v[72:73], v[84:85], v[42:43]
	s_nop 0
	v_cvt_pk_f16_f32 v20, v42, v43
	v_cvt_f32_f16_sdwa v43, v21 dst_sel:DWORD dst_unused:UNUSED_PAD src0_sel:WORD_1
	v_cvt_f32_f16_e32 v42, v21
	v_pk_fma_f32 v[42:43], v[74:75], v[68:69], v[42:43]
	s_nop 0
	v_cvt_pk_f16_f32 v21, v42, v43
	v_cvt_f32_f16_sdwa v43, v22 dst_sel:DWORD dst_unused:UNUSED_PAD src0_sel:WORD_1
	v_cvt_f32_f16_e32 v42, v22
	v_cvt_f32_f16_e32 v68, v70
	v_cvt_f32_f16_sdwa v69, v70 dst_sel:DWORD dst_unused:UNUSED_PAD src0_sel:WORD_1
	s_waitcnt lgkmcnt(0)
	v_pk_fma_f32 v[42:43], v[76:77], v[68:69], v[42:43]
	s_nop 0
	v_cvt_pk_f16_f32 v22, v42, v43
	v_cvt_f32_f16_sdwa v43, v23 dst_sel:DWORD dst_unused:UNUSED_PAD src0_sel:WORD_1
	v_cvt_f32_f16_e32 v42, v23
	v_cvt_f32_f16_e32 v68, v71
	v_cvt_f32_f16_sdwa v69, v71 dst_sel:DWORD dst_unused:UNUSED_PAD src0_sel:WORD_1
	s_waitcnt vmcnt(0)
	v_cvt_f32_f16_e32 v76, v64
	v_cvt_f32_f16_sdwa v77, v64 dst_sel:DWORD dst_unused:UNUSED_PAD src0_sel:WORD_1
	v_cvt_f32_f16_e32 v64, v65
	v_pk_fma_f32 v[42:43], v[78:79], v[68:69], v[42:43]
	ds_read_b128 v[68:71], v115 offset:6528
	ds_read_b128 v[72:75], v115 offset:6544
	v_cvt_pk_f16_f32 v23, v42, v43
	v_cvt_f32_f16_sdwa v43, v16 dst_sel:DWORD dst_unused:UNUSED_PAD src0_sel:WORD_1
	v_cvt_f32_f16_e32 v42, v16
	v_cvt_f32_f16_sdwa v65, v65 dst_sel:DWORD dst_unused:UNUSED_PAD src0_sel:WORD_1
	s_waitcnt lgkmcnt(1)
	v_pk_fma_f32 v[42:43], v[68:69], v[76:77], v[42:43]
	s_nop 0
	v_cvt_pk_f16_f32 v16, v42, v43
	v_cvt_f32_f16_sdwa v43, v17 dst_sel:DWORD dst_unused:UNUSED_PAD src0_sel:WORD_1
	v_cvt_f32_f16_e32 v42, v17
	v_pk_fma_f32 v[42:43], v[70:71], v[64:65], v[42:43]
	s_nop 0
	v_cvt_pk_f16_f32 v17, v42, v43
	v_cvt_f32_f16_sdwa v43, v18 dst_sel:DWORD dst_unused:UNUSED_PAD src0_sel:WORD_1
	v_cvt_f32_f16_e32 v42, v18
	v_cvt_f32_f16_e32 v64, v66
	v_cvt_f32_f16_sdwa v65, v66 dst_sel:DWORD dst_unused:UNUSED_PAD src0_sel:WORD_1
	s_waitcnt lgkmcnt(0)
	v_pk_fma_f32 v[42:43], v[72:73], v[64:65], v[42:43]
	s_nop 0
	v_cvt_pk_f16_f32 v18, v42, v43
	v_cvt_f32_f16_sdwa v43, v19 dst_sel:DWORD dst_unused:UNUSED_PAD src0_sel:WORD_1
	v_cvt_f32_f16_e32 v42, v19
	v_cvt_f32_f16_e32 v64, v67
	v_cvt_f32_f16_sdwa v65, v67 dst_sel:DWORD dst_unused:UNUSED_PAD src0_sel:WORD_1
	v_pk_fma_f32 v[42:43], v[74:75], v[64:65], v[42:43]
	s_nop 0
	v_cvt_pk_f16_f32 v19, v42, v43
	v_accvgpr_read_b32 v42, a200
	v_accvgpr_read_b32 v43, a201
	v_lshl_add_u64 v[42:43], v[42:43], 0, s[90:91]
	global_load_dwordx4 v[72:75], v[42:43], off
	v_accvgpr_read_b32 v42, a202
	v_accvgpr_read_b32 v43, a203
	v_lshl_add_u64 v[42:43], v[42:43], 0, s[90:91]
	global_load_dwordx4 v[76:79], v[42:43], off
	v_accvgpr_read_b32 v42, a204
	v_accvgpr_read_b32 v43, a205
	v_lshl_add_u64 v[42:43], v[42:43], 0, s[90:91]
	global_load_dwordx4 v[68:71], v[42:43], off
	v_lshl_add_u64 v[42:43], v[150:151], 0, s[90:91]
	global_load_dwordx4 v[64:67], v[42:43], off
	ds_write_b32 v89, a0
	ds_write_b32 v91, a16
	ds_write_b32 v89, a1 offset:272
	ds_write_b32 v91, a17 offset:272
	ds_write_b32 v89, a2 offset:544
	ds_write_b32 v91, a18 offset:544
	ds_write_b32 v93, a3
	ds_write_b32 v95, a19
	ds_write_b32 v89, a4 offset:2176
	ds_write_b32 v91, a20 offset:2176
	ds_write_b32 v89, a5 offset:2448
	ds_write_b32 v91, a21 offset:2448
	ds_write_b32 v89, a6 offset:2720
	ds_write_b32 v91, a22 offset:2720
	ds_write_b32 v97, a7
	ds_write_b32 v99, a23
	ds_write_b32 v89, a8 offset:4352
	ds_write_b32 v91, a24 offset:4352
	ds_write_b32 v89, a9 offset:4624
	ds_write_b32 v91, a25 offset:4624
	ds_write_b32 v89, a10 offset:4896
	ds_write_b32 v91, a26 offset:4896
	ds_write_b32 v101, a11
	ds_write_b32 v103, a27
	ds_write_b32 v89, a12 offset:6528
	ds_write_b32 v91, a28 offset:6528
	ds_write_b32 v89, a13 offset:6800
	ds_write_b32 v91, a29 offset:6800
	ds_write_b32 v89, a14 offset:7072
	ds_write_b32 v91, a30 offset:7072
	ds_write_b32 v105, a15
	ds_write_b32 v107, a31
	ds_read_b128 v[84:87], v115
	ds_read_b128 v[108:111], v115 offset:16
	v_cvt_f32_f16_sdwa v43, v12 dst_sel:DWORD dst_unused:UNUSED_PAD src0_sel:WORD_1
	v_cvt_f32_f16_e32 v42, v12
	s_waitcnt vmcnt(3)
	v_cvt_f32_f16_e32 v112, v72
	v_cvt_f32_f16_sdwa v113, v72 dst_sel:DWORD dst_unused:UNUSED_PAD src0_sel:WORD_1
	v_cvt_f32_f16_e32 v72, v73
	v_cvt_f32_f16_sdwa v73, v73 dst_sel:DWORD dst_unused:UNUSED_PAD src0_sel:WORD_1
	s_waitcnt lgkmcnt(1)
	v_pk_fma_f32 v[42:43], v[84:85], v[112:113], v[42:43]
	s_nop 0
	v_cvt_pk_f16_f32 v12, v42, v43
	v_cvt_f32_f16_sdwa v43, v13 dst_sel:DWORD dst_unused:UNUSED_PAD src0_sel:WORD_1
	v_cvt_f32_f16_e32 v42, v13
	v_pk_fma_f32 v[42:43], v[86:87], v[72:73], v[42:43]
	s_nop 0
	v_cvt_pk_f16_f32 v13, v42, v43
	v_cvt_f32_f16_sdwa v43, v14 dst_sel:DWORD dst_unused:UNUSED_PAD src0_sel:WORD_1
	v_cvt_f32_f16_e32 v42, v14
	v_cvt_f32_f16_e32 v72, v74
	v_cvt_f32_f16_sdwa v73, v74 dst_sel:DWORD dst_unused:UNUSED_PAD src0_sel:WORD_1
	s_waitcnt lgkmcnt(0)
	v_pk_fma_f32 v[42:43], v[108:109], v[72:73], v[42:43]
	s_nop 0
	v_cvt_pk_f16_f32 v14, v42, v43
	v_cvt_f32_f16_sdwa v43, v15 dst_sel:DWORD dst_unused:UNUSED_PAD src0_sel:WORD_1
	v_cvt_f32_f16_e32 v42, v15
	v_cvt_f32_f16_e32 v72, v75
	v_cvt_f32_f16_sdwa v73, v75 dst_sel:DWORD dst_unused:UNUSED_PAD src0_sel:WORD_1
	s_waitcnt vmcnt(2)
	v_cvt_f32_f16_e32 v108, v76
	v_cvt_f32_f16_sdwa v109, v76 dst_sel:DWORD dst_unused:UNUSED_PAD src0_sel:WORD_1
	v_pk_fma_f32 v[42:43], v[110:111], v[72:73], v[42:43]
	s_nop 0
	v_cvt_pk_f16_f32 v15, v42, v43
	ds_read_b128 v[72:75], v115 offset:2176
	ds_read_b128 v[84:87], v115 offset:2192
	v_cvt_f32_f16_sdwa v43, v8 dst_sel:DWORD dst_unused:UNUSED_PAD src0_sel:WORD_1
	v_cvt_f32_f16_e32 v42, v8
	s_waitcnt lgkmcnt(1)
	v_pk_fma_f32 v[42:43], v[72:73], v[108:109], v[42:43]
	s_nop 0
	v_cvt_pk_f16_f32 v8, v42, v43
	v_cvt_f32_f16_sdwa v43, v9 dst_sel:DWORD dst_unused:UNUSED_PAD src0_sel:WORD_1
	v_cvt_f32_f16_e32 v42, v9
	v_cvt_f32_f16_e32 v72, v77
	v_cvt_f32_f16_sdwa v73, v77 dst_sel:DWORD dst_unused:UNUSED_PAD src0_sel:WORD_1
	v_pk_fma_f32 v[42:43], v[74:75], v[72:73], v[42:43]
	s_nop 0
	v_cvt_pk_f16_f32 v9, v42, v43
	v_cvt_f32_f16_sdwa v43, v10 dst_sel:DWORD dst_unused:UNUSED_PAD src0_sel:WORD_1
	v_cvt_f32_f16_e32 v42, v10
	v_cvt_f32_f16_e32 v72, v78
	v_cvt_f32_f16_sdwa v73, v78 dst_sel:DWORD dst_unused:UNUSED_PAD src0_sel:WORD_1
	s_waitcnt lgkmcnt(0)
	v_pk_fma_f32 v[42:43], v[84:85], v[72:73], v[42:43]
	s_nop 0
	v_cvt_pk_f16_f32 v10, v42, v43
	v_cvt_f32_f16_sdwa v43, v11 dst_sel:DWORD dst_unused:UNUSED_PAD src0_sel:WORD_1
	v_cvt_f32_f16_e32 v42, v11
	v_cvt_f32_f16_e32 v72, v79
	v_cvt_f32_f16_sdwa v73, v79 dst_sel:DWORD dst_unused:UNUSED_PAD src0_sel:WORD_1
	s_waitcnt vmcnt(1)
	v_cvt_f32_f16_e32 v84, v68
	v_cvt_f32_f16_sdwa v85, v68 dst_sel:DWORD dst_unused:UNUSED_PAD src0_sel:WORD_1
	v_cvt_f32_f16_e32 v68, v69
	v_pk_fma_f32 v[42:43], v[86:87], v[72:73], v[42:43]
	ds_read_b128 v[72:75], v115 offset:4352
	ds_read_b128 v[76:79], v115 offset:4368
	v_cvt_pk_f16_f32 v11, v42, v43
	v_cvt_f32_f16_sdwa v43, v4 dst_sel:DWORD dst_unused:UNUSED_PAD src0_sel:WORD_1
	v_cvt_f32_f16_e32 v42, v4
	v_cvt_f32_f16_sdwa v69, v69 dst_sel:DWORD dst_unused:UNUSED_PAD src0_sel:WORD_1
	s_waitcnt lgkmcnt(1)
	v_pk_fma_f32 v[42:43], v[72:73], v[84:85], v[42:43]
	s_nop 0
	v_cvt_pk_f16_f32 v4, v42, v43
	v_cvt_f32_f16_sdwa v43, v5 dst_sel:DWORD dst_unused:UNUSED_PAD src0_sel:WORD_1
	v_cvt_f32_f16_e32 v42, v5
	v_pk_fma_f32 v[42:43], v[74:75], v[68:69], v[42:43]
	s_nop 0
	v_cvt_pk_f16_f32 v5, v42, v43
	v_cvt_f32_f16_sdwa v43, v6 dst_sel:DWORD dst_unused:UNUSED_PAD src0_sel:WORD_1
	v_cvt_f32_f16_e32 v42, v6
	v_cvt_f32_f16_e32 v68, v70
	v_cvt_f32_f16_sdwa v69, v70 dst_sel:DWORD dst_unused:UNUSED_PAD src0_sel:WORD_1
	s_waitcnt lgkmcnt(0)
	v_pk_fma_f32 v[42:43], v[76:77], v[68:69], v[42:43]
	s_nop 0
	v_cvt_pk_f16_f32 v6, v42, v43
	v_cvt_f32_f16_sdwa v43, v7 dst_sel:DWORD dst_unused:UNUSED_PAD src0_sel:WORD_1
	v_cvt_f32_f16_e32 v42, v7
	v_cvt_f32_f16_e32 v68, v71
	v_cvt_f32_f16_sdwa v69, v71 dst_sel:DWORD dst_unused:UNUSED_PAD src0_sel:WORD_1
	s_waitcnt vmcnt(0)
	v_cvt_f32_f16_e32 v76, v64
	v_cvt_f32_f16_sdwa v77, v64 dst_sel:DWORD dst_unused:UNUSED_PAD src0_sel:WORD_1
	v_cvt_f32_f16_e32 v64, v65
	v_pk_fma_f32 v[42:43], v[78:79], v[68:69], v[42:43]
	ds_read_b128 v[68:71], v115 offset:6528
	ds_read_b128 v[72:75], v115 offset:6544
	v_cvt_pk_f16_f32 v7, v42, v43
	v_cvt_f32_f16_sdwa v43, v0 dst_sel:DWORD dst_unused:UNUSED_PAD src0_sel:WORD_1
	v_cvt_f32_f16_e32 v42, v0
	v_cvt_f32_f16_sdwa v65, v65 dst_sel:DWORD dst_unused:UNUSED_PAD src0_sel:WORD_1
	s_waitcnt lgkmcnt(1)
	v_pk_fma_f32 v[42:43], v[68:69], v[76:77], v[42:43]
	s_nop 0
	v_cvt_pk_f16_f32 v0, v42, v43
	v_cvt_f32_f16_sdwa v43, v1 dst_sel:DWORD dst_unused:UNUSED_PAD src0_sel:WORD_1
	v_cvt_f32_f16_e32 v42, v1
	v_pk_fma_f32 v[42:43], v[70:71], v[64:65], v[42:43]
	s_nop 0
	v_cvt_pk_f16_f32 v1, v42, v43
	v_cvt_f32_f16_sdwa v43, v2 dst_sel:DWORD dst_unused:UNUSED_PAD src0_sel:WORD_1
	v_cvt_f32_f16_e32 v42, v2
	v_cvt_f32_f16_e32 v64, v66
	v_cvt_f32_f16_sdwa v65, v66 dst_sel:DWORD dst_unused:UNUSED_PAD src0_sel:WORD_1
	s_waitcnt lgkmcnt(0)
	v_pk_fma_f32 v[42:43], v[72:73], v[64:65], v[42:43]
	s_nop 0
	v_cvt_pk_f16_f32 v2, v42, v43
	v_cvt_f32_f16_sdwa v43, v3 dst_sel:DWORD dst_unused:UNUSED_PAD src0_sel:WORD_1
	v_cvt_f32_f16_e32 v42, v3
	v_cvt_f32_f16_e32 v64, v67
	v_cvt_f32_f16_sdwa v65, v67 dst_sel:DWORD dst_unused:UNUSED_PAD src0_sel:WORD_1
	v_pk_fma_f32 v[42:43], v[74:75], v[64:65], v[42:43]
	s_nop 0
	v_cvt_pk_f16_f32 v3, v42, v43
	s_cbranch_scc0 .LBB0_67
	v_readlane_b32 s2, v253, 27
	v_accvgpr_read_b32 v42, a160
	v_readlane_b32 s3, v253, 28
	v_accvgpr_read_b32 v43, a161
	v_accvgpr_read_b32 v40, a162
	v_lshl_add_u64 v[42:43], v[42:43], 1, s[2:3]
	v_mad_i64_i32 v[64:65], s[2:3], v40, s33, v[42:43]
	v_accvgpr_read_b32 v40, a164
	global_store_dwordx4 v[64:65], v[60:63], off
	s_nop 1
	v_mad_i64_i32 v[60:61], s[2:3], v40, s33, v[42:43]
	v_accvgpr_read_b32 v40, a166
	global_store_dwordx4 v[60:61], v[56:59], off
	s_nop 1
	v_mad_i64_i32 v[56:57], s[2:3], v40, s33, v[42:43]
	global_store_dwordx4 v[56:57], v[52:55], off
	s_nop 1
	v_mad_i64_i32 v[52:53], s[2:3], v90, s33, v[42:43]
	global_store_dwordx4 v[52:53], v[48:51], off
	s_nop 1
	v_mad_i64_i32 v[48:49], s[2:3], v92, s33, v[42:43]
	global_store_dwordx4 v[48:49], v[44:47], off
	s_nop 1
	v_mad_i64_i32 v[44:45], s[2:3], v94, s33, v[42:43]
	global_store_dwordx4 v[44:45], v[180:183], off
	v_mad_i64_i32 v[44:45], s[2:3], v96, s33, v[42:43]
	global_store_dwordx4 v[44:45], v[36:39], off
	s_nop 1
	v_mad_i64_i32 v[36:37], s[2:3], v98, s33, v[42:43]
	global_store_dwordx4 v[36:37], v[32:35], off
	s_nop 1
	v_mad_i64_i32 v[32:33], s[2:3], v100, s33, v[42:43]
	global_store_dwordx4 v[32:33], v[28:31], off
	s_nop 1
	v_mad_i64_i32 v[28:29], s[2:3], v102, s33, v[42:43]
	global_store_dwordx4 v[28:29], v[24:27], off
	s_nop 1
	v_mad_i64_i32 v[24:25], s[2:3], v104, s33, v[42:43]
	global_store_dwordx4 v[24:25], v[20:23], off
	s_nop 1
	v_mad_i64_i32 v[20:21], s[2:3], v106, s33, v[42:43]
	global_store_dwordx4 v[20:21], v[16:19], off
	s_nop 1
	v_accvgpr_read_b32 v16, a168
	v_mad_i64_i32 v[16:17], s[2:3], v16, s33, v[42:43]
	global_store_dwordx4 v[16:17], v[12:15], off
	s_nop 1
	v_accvgpr_read_b32 v12, a170
	v_mad_i64_i32 v[12:13], s[2:3], v12, s33, v[42:43]
	global_store_dwordx4 v[12:13], v[8:11], off
	s_nop 1
	v_mad_i64_i32 v[8:9], s[2:3], v114, s33, v[42:43]
	global_store_dwordx4 v[8:9], v[4:7], off
	v_accvgpr_read_b32 v8, a157
	s_nop 0
	v_mad_i64_i32 v[4:5], s[2:3], v116, s33, v[42:43]
	global_store_dwordx4 v[4:5], v[0:3], off
	s_branch .LBB0_60
